# consumer keeps S_t/g_t (decay folded into the column vectors, state renormalised every 32-step block), operands fetched two steps ahead; RG-LRU in producer waves
# speedup vs baseline: 1.0319x; 1.0044x over previous
.LBB0_916:
	s_and_b64 vcc, exec, s[4:5]
	s_cbranch_vccz .LBB0_871
	s_and_b32 s4, s83, 0xfffff800
	s_ashr_i32 s5, s4, 31
	s_and_b32 s6, s90, 7
	s_lshl_b64 s[4:5], s[4:5], 10
	s_lshl_b32 s6, s6, 7
	s_waitcnt lgkmcnt(0)
	s_barrier
	s_or_b32 s4, s4, s6
	v_lshl_add_u64 v[0:1], v[40:41], 0, s[4:5]
	v_mov_b32_e32 v4, 0
	s_mov_b32 s6, 0
	v_mov_b32_e32 v5, 0
	v_mov_b32_e32 v6, 0
	v_mov_b32_e32 v7, 0
	v_mov_b32_e32 v8, 0
	v_mov_b32_e32 v9, 0
	v_mov_b32_e32 v10, 0
	v_mov_b32_e32 v11, 0
	s_waitcnt vmcnt(0)
	v_mov_b32_e32 v12, 0
	v_mov_b32_e32 v13, 0
	v_mov_b32_e32 v14, 0
	v_mov_b32_e32 v15, 0
	v_mov_b32_e32 v16, 0
	v_mov_b32_e32 v17, 0
	v_mov_b32_e32 v18, 0
	v_mov_b32_e32 v19, 0
	s_add_u32 s4, s4, s96
	s_addc_u32 s5, s5, s97
	s_add_u32 s4, s4, 0x1d800000
	s_addc_u32 s5, s5, 0
	v_add_u32_e32 v52, 0xfffffb00, v38
	v_lshrrev_b32_e32 v52, 1, v52
	v_lshrrev_b32_e32 v53, 4, v32
	v_and_b32_e32 v54, 1, v53
	v_lshrrev_b32_e32 v53, 1, v53
	v_lshl_or_b32 v53, v54, 1, v53
	v_lshl_add_u32 v52, v53, 10, v52
	v_mov_b32_e32 v82, 1.0
.Lsc_blk:
	s_bitcmp1_b32 s6, 0
	s_cselect_b32 s7, 0xc000, 0
	v_add_u32_e32 v2, s7, v38
	v_add_u32_e32 v3, s7, v56
	s_mov_b32 s7, 0
	s_nop 0
	ds_read2st64_b32 v[20:21], v3 offset0:0 offset1:1
	ds_read2st64_b32 v[22:23], v3 offset0:2 offset1:3
	ds_read_b32 v24, v3 offset:1024
	ds_read_b32 v84, v2 offset:0
	ds_read2st64_b32 v[26:27], v3 offset0:6 offset1:7
	ds_read2st64_b32 v[28:29], v3 offset0:8 offset1:9
	ds_read_b32 v30, v3 offset:2560
	ds_read_b32 v85, v2 offset:1536
	v_mul_f32_dpp v4, v82, v4 row_newbcast:0 row_mask:0xf bank_mask:0xf
	v_mul_f32_dpp v5, v82, v5 row_newbcast:1 row_mask:0xf bank_mask:0xf
	v_mul_f32_dpp v6, v82, v6 row_newbcast:2 row_mask:0xf bank_mask:0xf
	v_mul_f32_dpp v7, v82, v7 row_newbcast:3 row_mask:0xf bank_mask:0xf
	v_mul_f32_dpp v8, v82, v8 row_newbcast:4 row_mask:0xf bank_mask:0xf
	v_mul_f32_dpp v9, v82, v9 row_newbcast:5 row_mask:0xf bank_mask:0xf
	v_mul_f32_dpp v10, v82, v10 row_newbcast:6 row_mask:0xf bank_mask:0xf
	v_mul_f32_dpp v11, v82, v11 row_newbcast:7 row_mask:0xf bank_mask:0xf
	v_mul_f32_dpp v12, v82, v12 row_newbcast:8 row_mask:0xf bank_mask:0xf
	v_mul_f32_dpp v13, v82, v13 row_newbcast:9 row_mask:0xf bank_mask:0xf
	v_mul_f32_dpp v14, v82, v14 row_newbcast:10 row_mask:0xf bank_mask:0xf
	v_mul_f32_dpp v15, v82, v15 row_newbcast:11 row_mask:0xf bank_mask:0xf
	v_mul_f32_dpp v16, v82, v16 row_newbcast:12 row_mask:0xf bank_mask:0xf
	v_mul_f32_dpp v17, v82, v17 row_newbcast:13 row_mask:0xf bank_mask:0xf
	v_mul_f32_dpp v18, v82, v18 row_newbcast:14 row_mask:0xf bank_mask:0xf
	v_mul_f32_dpp v19, v82, v19 row_newbcast:15 row_mask:0xf bank_mask:0xf
	v_mov_b32_e32 v82, 1.0
	s_waitcnt lgkmcnt(0)
	v_mul_f32_e32 v73, v20, v82
	v_mul_f32_e32 v81, v82, v23
	v_mul_f32_e32 v76, v24, v81
	v_rcp_f32_e32 v83, v81
	s_nop 0
	v_mul_f32_e32 v75, v22, v83
	v_mul_f32_e32 v74, v21, v83
	s_nop 1
.Lsc_it:
	ds_read2st64_b32 v[20:21], v3 offset0:12 offset1:13
	ds_read2st64_b32 v[22:23], v3 offset0:14 offset1:15
	ds_read_b32 v24, v3 offset:4096
	ds_read_b32 v86, v2 offset:3072
	v_mul_f32_dpp v0, v73, v4 row_newbcast:0 row_mask:0xf bank_mask:0xf
	v_mul_f32_dpp v1, v73, v5 row_newbcast:1 row_mask:0xf bank_mask:0xf
	v_fmac_f32_dpp v4, v75, v84 row_newbcast:0 row_mask:0xf bank_mask:0xf
	v_fmac_f32_dpp v0, v73, v6 row_newbcast:2 row_mask:0xf bank_mask:0xf
	v_fmac_f32_dpp v5, v75, v84 row_newbcast:1 row_mask:0xf bank_mask:0xf
	v_fmac_f32_dpp v1, v73, v7 row_newbcast:3 row_mask:0xf bank_mask:0xf
	v_fmac_f32_dpp v6, v75, v84 row_newbcast:2 row_mask:0xf bank_mask:0xf
	v_fmac_f32_dpp v0, v73, v8 row_newbcast:4 row_mask:0xf bank_mask:0xf
	v_fmac_f32_dpp v7, v75, v84 row_newbcast:3 row_mask:0xf bank_mask:0xf
	v_fmac_f32_dpp v1, v73, v9 row_newbcast:5 row_mask:0xf bank_mask:0xf
	v_fmac_f32_dpp v8, v75, v84 row_newbcast:4 row_mask:0xf bank_mask:0xf
	v_fmac_f32_dpp v0, v73, v10 row_newbcast:6 row_mask:0xf bank_mask:0xf
	v_fmac_f32_dpp v9, v75, v84 row_newbcast:5 row_mask:0xf bank_mask:0xf
	v_fmac_f32_dpp v1, v73, v11 row_newbcast:7 row_mask:0xf bank_mask:0xf
	v_fmac_f32_dpp v10, v75, v84 row_newbcast:6 row_mask:0xf bank_mask:0xf
	v_fmac_f32_dpp v0, v73, v12 row_newbcast:8 row_mask:0xf bank_mask:0xf
	v_fmac_f32_dpp v11, v75, v84 row_newbcast:7 row_mask:0xf bank_mask:0xf
	v_fmac_f32_dpp v1, v73, v13 row_newbcast:9 row_mask:0xf bank_mask:0xf
	v_fmac_f32_dpp v12, v75, v84 row_newbcast:8 row_mask:0xf bank_mask:0xf
	v_fmac_f32_dpp v0, v73, v14 row_newbcast:10 row_mask:0xf bank_mask:0xf
	v_fmac_f32_dpp v13, v75, v84 row_newbcast:9 row_mask:0xf bank_mask:0xf
	v_fmac_f32_dpp v1, v73, v15 row_newbcast:11 row_mask:0xf bank_mask:0xf
	v_fmac_f32_dpp v14, v75, v84 row_newbcast:10 row_mask:0xf bank_mask:0xf
	v_fmac_f32_dpp v0, v73, v16 row_newbcast:12 row_mask:0xf bank_mask:0xf
	v_fmac_f32_dpp v15, v75, v84 row_newbcast:11 row_mask:0xf bank_mask:0xf
	v_fmac_f32_dpp v1, v73, v17 row_newbcast:13 row_mask:0xf bank_mask:0xf
	v_fmac_f32_dpp v16, v75, v84 row_newbcast:12 row_mask:0xf bank_mask:0xf
	v_fmac_f32_dpp v0, v73, v18 row_newbcast:14 row_mask:0xf bank_mask:0xf
	v_fmac_f32_dpp v17, v75, v84 row_newbcast:13 row_mask:0xf bank_mask:0xf
	v_fmac_f32_dpp v1, v73, v19 row_newbcast:15 row_mask:0xf bank_mask:0xf
	v_fmac_f32_dpp v18, v75, v84 row_newbcast:14 row_mask:0xf bank_mask:0xf
	v_fmac_f32_dpp v19, v75, v84 row_newbcast:15 row_mask:0xf bank_mask:0xf
	v_add_f32_e32 v68, v0, v1
	v_add_f32_e32 v69, v0, v1
	s_waitcnt lgkmcnt(4)
	v_mul_f32_e32 v77, v26, v81
	v_permlane32_swap_b32_e32 v68, v69
	v_mul_f32_e32 v82, v81, v29
	v_add_f32_e32 v70, v68, v69
	v_add_f32_e32 v71, v68, v69
	v_rcp_f32_e32 v83, v82
	v_mul_f32_e32 v80, v30, v82
	v_permlane16_swap_b32_e32 v70, v71
	v_add_f32_e32 v72, v70, v71
	v_mul_f32_e32 v79, v28, v83
	v_mul_f32_e32 v78, v27, v83
	v_fmac_f32_dpp v4, v74, v72 row_newbcast:0 row_mask:0xf bank_mask:0xf
	v_fmac_f32_dpp v5, v74, v72 row_newbcast:1 row_mask:0xf bank_mask:0xf
	v_fmac_f32_dpp v6, v74, v72 row_newbcast:2 row_mask:0xf bank_mask:0xf
	v_mul_f32_dpp v60, v76, v4 row_newbcast:0 row_mask:0xf bank_mask:0xf
	v_fmac_f32_dpp v7, v74, v72 row_newbcast:3 row_mask:0xf bank_mask:0xf
	v_mul_f32_dpp v61, v76, v5 row_newbcast:1 row_mask:0xf bank_mask:0xf
	v_fmac_f32_dpp v8, v74, v72 row_newbcast:4 row_mask:0xf bank_mask:0xf
	v_fmac_f32_dpp v60, v76, v6 row_newbcast:2 row_mask:0xf bank_mask:0xf
	v_fmac_f32_dpp v9, v74, v72 row_newbcast:5 row_mask:0xf bank_mask:0xf
	v_fmac_f32_dpp v61, v76, v7 row_newbcast:3 row_mask:0xf bank_mask:0xf
	v_fmac_f32_dpp v10, v74, v72 row_newbcast:6 row_mask:0xf bank_mask:0xf
	v_fmac_f32_dpp v60, v76, v8 row_newbcast:4 row_mask:0xf bank_mask:0xf
	v_fmac_f32_dpp v11, v74, v72 row_newbcast:7 row_mask:0xf bank_mask:0xf
	v_fmac_f32_dpp v61, v76, v9 row_newbcast:5 row_mask:0xf bank_mask:0xf
	v_fmac_f32_dpp v12, v74, v72 row_newbcast:8 row_mask:0xf bank_mask:0xf
	v_fmac_f32_dpp v60, v76, v10 row_newbcast:6 row_mask:0xf bank_mask:0xf
	v_fmac_f32_dpp v13, v74, v72 row_newbcast:9 row_mask:0xf bank_mask:0xf
	v_fmac_f32_dpp v61, v76, v11 row_newbcast:7 row_mask:0xf bank_mask:0xf
	v_fmac_f32_dpp v14, v74, v72 row_newbcast:10 row_mask:0xf bank_mask:0xf
	v_fmac_f32_dpp v60, v76, v12 row_newbcast:8 row_mask:0xf bank_mask:0xf
	v_fmac_f32_dpp v15, v74, v72 row_newbcast:11 row_mask:0xf bank_mask:0xf
	v_fmac_f32_dpp v61, v76, v13 row_newbcast:9 row_mask:0xf bank_mask:0xf
	v_fmac_f32_dpp v16, v74, v72 row_newbcast:12 row_mask:0xf bank_mask:0xf
	v_fmac_f32_dpp v60, v76, v14 row_newbcast:10 row_mask:0xf bank_mask:0xf
	v_fmac_f32_dpp v17, v74, v72 row_newbcast:13 row_mask:0xf bank_mask:0xf
	v_fmac_f32_dpp v61, v76, v15 row_newbcast:11 row_mask:0xf bank_mask:0xf
	v_fmac_f32_dpp v18, v74, v72 row_newbcast:14 row_mask:0xf bank_mask:0xf
	v_fmac_f32_dpp v60, v76, v16 row_newbcast:12 row_mask:0xf bank_mask:0xf
	v_fmac_f32_dpp v19, v74, v72 row_newbcast:15 row_mask:0xf bank_mask:0xf
	v_fmac_f32_dpp v61, v76, v17 row_newbcast:13 row_mask:0xf bank_mask:0xf
	v_fmac_f32_dpp v60, v76, v18 row_newbcast:14 row_mask:0xf bank_mask:0xf
	v_fmac_f32_dpp v61, v76, v19 row_newbcast:15 row_mask:0xf bank_mask:0xf
	ds_read2st64_b32 v[26:27], v3 offset0:18 offset1:19
	ds_read2st64_b32 v[28:29], v3 offset0:20 offset1:21
	ds_read_b32 v30, v3 offset:5632
	ds_read_b32 v87, v2 offset:4608
	v_mul_f32_dpp v0, v77, v4 row_newbcast:0 row_mask:0xf bank_mask:0xf
	v_mul_f32_dpp v1, v77, v5 row_newbcast:1 row_mask:0xf bank_mask:0xf
	v_fmac_f32_dpp v4, v79, v85 row_newbcast:0 row_mask:0xf bank_mask:0xf
	v_fmac_f32_dpp v0, v77, v6 row_newbcast:2 row_mask:0xf bank_mask:0xf
	v_fmac_f32_dpp v5, v79, v85 row_newbcast:1 row_mask:0xf bank_mask:0xf
	v_fmac_f32_dpp v1, v77, v7 row_newbcast:3 row_mask:0xf bank_mask:0xf
	v_fmac_f32_dpp v6, v79, v85 row_newbcast:2 row_mask:0xf bank_mask:0xf
	v_fmac_f32_dpp v0, v77, v8 row_newbcast:4 row_mask:0xf bank_mask:0xf
	v_fmac_f32_dpp v7, v79, v85 row_newbcast:3 row_mask:0xf bank_mask:0xf
	v_fmac_f32_dpp v1, v77, v9 row_newbcast:5 row_mask:0xf bank_mask:0xf
	v_fmac_f32_dpp v8, v79, v85 row_newbcast:4 row_mask:0xf bank_mask:0xf
	v_fmac_f32_dpp v0, v77, v10 row_newbcast:6 row_mask:0xf bank_mask:0xf
	v_fmac_f32_dpp v9, v79, v85 row_newbcast:5 row_mask:0xf bank_mask:0xf
	v_fmac_f32_dpp v1, v77, v11 row_newbcast:7 row_mask:0xf bank_mask:0xf
	v_fmac_f32_dpp v10, v79, v85 row_newbcast:6 row_mask:0xf bank_mask:0xf
	v_fmac_f32_dpp v0, v77, v12 row_newbcast:8 row_mask:0xf bank_mask:0xf
	v_fmac_f32_dpp v11, v79, v85 row_newbcast:7 row_mask:0xf bank_mask:0xf
	v_fmac_f32_dpp v1, v77, v13 row_newbcast:9 row_mask:0xf bank_mask:0xf
	v_fmac_f32_dpp v12, v79, v85 row_newbcast:8 row_mask:0xf bank_mask:0xf
	v_fmac_f32_dpp v0, v77, v14 row_newbcast:10 row_mask:0xf bank_mask:0xf
	v_fmac_f32_dpp v13, v79, v85 row_newbcast:9 row_mask:0xf bank_mask:0xf
	v_fmac_f32_dpp v1, v77, v15 row_newbcast:11 row_mask:0xf bank_mask:0xf
	v_fmac_f32_dpp v14, v79, v85 row_newbcast:10 row_mask:0xf bank_mask:0xf
	v_fmac_f32_dpp v0, v77, v16 row_newbcast:12 row_mask:0xf bank_mask:0xf
	v_fmac_f32_dpp v15, v79, v85 row_newbcast:11 row_mask:0xf bank_mask:0xf
	v_fmac_f32_dpp v1, v77, v17 row_newbcast:13 row_mask:0xf bank_mask:0xf
	v_fmac_f32_dpp v16, v79, v85 row_newbcast:12 row_mask:0xf bank_mask:0xf
	v_fmac_f32_dpp v0, v77, v18 row_newbcast:14 row_mask:0xf bank_mask:0xf
	v_fmac_f32_dpp v17, v79, v85 row_newbcast:13 row_mask:0xf bank_mask:0xf
	v_fmac_f32_dpp v1, v77, v19 row_newbcast:15 row_mask:0xf bank_mask:0xf
	v_fmac_f32_dpp v18, v79, v85 row_newbcast:14 row_mask:0xf bank_mask:0xf
	v_fmac_f32_dpp v19, v79, v85 row_newbcast:15 row_mask:0xf bank_mask:0xf
	v_add_f32_e32 v68, v0, v1
	v_add_f32_e32 v69, v0, v1
	s_waitcnt lgkmcnt(4)
	v_mul_f32_e32 v73, v20, v82
	v_permlane32_swap_b32_e32 v68, v69
	v_mul_f32_e32 v81, v82, v23
	v_add_f32_e32 v70, v68, v69
	v_add_f32_e32 v71, v68, v69
	v_rcp_f32_e32 v83, v81
	v_mul_f32_e32 v76, v24, v81
	v_permlane16_swap_b32_e32 v70, v71
	v_add_f32_e32 v72, v70, v71
	v_mul_f32_e32 v75, v22, v83
	v_mul_f32_e32 v74, v21, v83
	v_fmac_f32_dpp v4, v78, v72 row_newbcast:0 row_mask:0xf bank_mask:0xf
	v_fmac_f32_dpp v5, v78, v72 row_newbcast:1 row_mask:0xf bank_mask:0xf
	v_fmac_f32_dpp v6, v78, v72 row_newbcast:2 row_mask:0xf bank_mask:0xf
	v_mul_f32_dpp v62, v80, v4 row_newbcast:0 row_mask:0xf bank_mask:0xf
	v_fmac_f32_dpp v7, v78, v72 row_newbcast:3 row_mask:0xf bank_mask:0xf
	v_mul_f32_dpp v63, v80, v5 row_newbcast:1 row_mask:0xf bank_mask:0xf
	v_fmac_f32_dpp v8, v78, v72 row_newbcast:4 row_mask:0xf bank_mask:0xf
	v_fmac_f32_dpp v62, v80, v6 row_newbcast:2 row_mask:0xf bank_mask:0xf
	v_fmac_f32_dpp v9, v78, v72 row_newbcast:5 row_mask:0xf bank_mask:0xf
	v_fmac_f32_dpp v63, v80, v7 row_newbcast:3 row_mask:0xf bank_mask:0xf
	v_fmac_f32_dpp v10, v78, v72 row_newbcast:6 row_mask:0xf bank_mask:0xf
	v_fmac_f32_dpp v62, v80, v8 row_newbcast:4 row_mask:0xf bank_mask:0xf
	v_fmac_f32_dpp v11, v78, v72 row_newbcast:7 row_mask:0xf bank_mask:0xf
	v_fmac_f32_dpp v63, v80, v9 row_newbcast:5 row_mask:0xf bank_mask:0xf
	v_fmac_f32_dpp v12, v78, v72 row_newbcast:8 row_mask:0xf bank_mask:0xf
	v_fmac_f32_dpp v62, v80, v10 row_newbcast:6 row_mask:0xf bank_mask:0xf
	v_fmac_f32_dpp v13, v78, v72 row_newbcast:9 row_mask:0xf bank_mask:0xf
	v_fmac_f32_dpp v63, v80, v11 row_newbcast:7 row_mask:0xf bank_mask:0xf
	v_fmac_f32_dpp v14, v78, v72 row_newbcast:10 row_mask:0xf bank_mask:0xf
	v_fmac_f32_dpp v62, v80, v12 row_newbcast:8 row_mask:0xf bank_mask:0xf
	v_fmac_f32_dpp v15, v78, v72 row_newbcast:11 row_mask:0xf bank_mask:0xf
	v_fmac_f32_dpp v63, v80, v13 row_newbcast:9 row_mask:0xf bank_mask:0xf
	v_fmac_f32_dpp v16, v78, v72 row_newbcast:12 row_mask:0xf bank_mask:0xf
	v_fmac_f32_dpp v62, v80, v14 row_newbcast:10 row_mask:0xf bank_mask:0xf
	v_fmac_f32_dpp v17, v78, v72 row_newbcast:13 row_mask:0xf bank_mask:0xf
	v_fmac_f32_dpp v63, v80, v15 row_newbcast:11 row_mask:0xf bank_mask:0xf
	v_fmac_f32_dpp v18, v78, v72 row_newbcast:14 row_mask:0xf bank_mask:0xf
	v_fmac_f32_dpp v62, v80, v16 row_newbcast:12 row_mask:0xf bank_mask:0xf
	v_fmac_f32_dpp v19, v78, v72 row_newbcast:15 row_mask:0xf bank_mask:0xf
	v_fmac_f32_dpp v63, v80, v17 row_newbcast:13 row_mask:0xf bank_mask:0xf
	v_fmac_f32_dpp v62, v80, v18 row_newbcast:14 row_mask:0xf bank_mask:0xf
	v_fmac_f32_dpp v63, v80, v19 row_newbcast:15 row_mask:0xf bank_mask:0xf
	ds_read2st64_b32 v[20:21], v3 offset0:24 offset1:25
	ds_read2st64_b32 v[22:23], v3 offset0:26 offset1:27
	ds_read_b32 v24, v3 offset:7168
	ds_read_b32 v84, v2 offset:6144
	v_mul_f32_dpp v0, v73, v4 row_newbcast:0 row_mask:0xf bank_mask:0xf
	v_mul_f32_dpp v1, v73, v5 row_newbcast:1 row_mask:0xf bank_mask:0xf
	v_fmac_f32_dpp v4, v75, v86 row_newbcast:0 row_mask:0xf bank_mask:0xf
	v_fmac_f32_dpp v0, v73, v6 row_newbcast:2 row_mask:0xf bank_mask:0xf
	v_fmac_f32_dpp v5, v75, v86 row_newbcast:1 row_mask:0xf bank_mask:0xf
	v_fmac_f32_dpp v1, v73, v7 row_newbcast:3 row_mask:0xf bank_mask:0xf
	v_fmac_f32_dpp v6, v75, v86 row_newbcast:2 row_mask:0xf bank_mask:0xf
	v_fmac_f32_dpp v0, v73, v8 row_newbcast:4 row_mask:0xf bank_mask:0xf
	v_fmac_f32_dpp v7, v75, v86 row_newbcast:3 row_mask:0xf bank_mask:0xf
	v_fmac_f32_dpp v1, v73, v9 row_newbcast:5 row_mask:0xf bank_mask:0xf
	v_fmac_f32_dpp v8, v75, v86 row_newbcast:4 row_mask:0xf bank_mask:0xf
	v_fmac_f32_dpp v0, v73, v10 row_newbcast:6 row_mask:0xf bank_mask:0xf
	v_fmac_f32_dpp v9, v75, v86 row_newbcast:5 row_mask:0xf bank_mask:0xf
	v_fmac_f32_dpp v1, v73, v11 row_newbcast:7 row_mask:0xf bank_mask:0xf
	v_fmac_f32_dpp v10, v75, v86 row_newbcast:6 row_mask:0xf bank_mask:0xf
	v_fmac_f32_dpp v0, v73, v12 row_newbcast:8 row_mask:0xf bank_mask:0xf
	v_fmac_f32_dpp v11, v75, v86 row_newbcast:7 row_mask:0xf bank_mask:0xf
	v_fmac_f32_dpp v1, v73, v13 row_newbcast:9 row_mask:0xf bank_mask:0xf
	v_fmac_f32_dpp v12, v75, v86 row_newbcast:8 row_mask:0xf bank_mask:0xf
	v_fmac_f32_dpp v0, v73, v14 row_newbcast:10 row_mask:0xf bank_mask:0xf
	v_fmac_f32_dpp v13, v75, v86 row_newbcast:9 row_mask:0xf bank_mask:0xf
	v_fmac_f32_dpp v1, v73, v15 row_newbcast:11 row_mask:0xf bank_mask:0xf
	v_fmac_f32_dpp v14, v75, v86 row_newbcast:10 row_mask:0xf bank_mask:0xf
	v_fmac_f32_dpp v0, v73, v16 row_newbcast:12 row_mask:0xf bank_mask:0xf
	v_fmac_f32_dpp v15, v75, v86 row_newbcast:11 row_mask:0xf bank_mask:0xf
	v_fmac_f32_dpp v1, v73, v17 row_newbcast:13 row_mask:0xf bank_mask:0xf
	v_fmac_f32_dpp v16, v75, v86 row_newbcast:12 row_mask:0xf bank_mask:0xf
	v_fmac_f32_dpp v0, v73, v18 row_newbcast:14 row_mask:0xf bank_mask:0xf
	v_fmac_f32_dpp v17, v75, v86 row_newbcast:13 row_mask:0xf bank_mask:0xf
	v_fmac_f32_dpp v1, v73, v19 row_newbcast:15 row_mask:0xf bank_mask:0xf
	v_fmac_f32_dpp v18, v75, v86 row_newbcast:14 row_mask:0xf bank_mask:0xf
	v_fmac_f32_dpp v19, v75, v86 row_newbcast:15 row_mask:0xf bank_mask:0xf
	v_add_f32_e32 v68, v0, v1
	v_add_f32_e32 v69, v0, v1
	s_waitcnt lgkmcnt(4)
	v_mul_f32_e32 v77, v26, v81
	v_permlane32_swap_b32_e32 v68, v69
	v_mul_f32_e32 v82, v81, v29
	v_add_f32_e32 v70, v68, v69
	v_add_f32_e32 v71, v68, v69
	v_rcp_f32_e32 v83, v82
	v_mul_f32_e32 v80, v30, v82
	v_permlane16_swap_b32_e32 v70, v71
	v_add_f32_e32 v72, v70, v71
	v_mul_f32_e32 v79, v28, v83
	v_mul_f32_e32 v78, v27, v83
	v_fmac_f32_dpp v4, v74, v72 row_newbcast:0 row_mask:0xf bank_mask:0xf
	v_fmac_f32_dpp v5, v74, v72 row_newbcast:1 row_mask:0xf bank_mask:0xf
	v_fmac_f32_dpp v6, v74, v72 row_newbcast:2 row_mask:0xf bank_mask:0xf
	v_mul_f32_dpp v64, v76, v4 row_newbcast:0 row_mask:0xf bank_mask:0xf
	v_fmac_f32_dpp v7, v74, v72 row_newbcast:3 row_mask:0xf bank_mask:0xf
	v_mul_f32_dpp v65, v76, v5 row_newbcast:1 row_mask:0xf bank_mask:0xf
	v_fmac_f32_dpp v8, v74, v72 row_newbcast:4 row_mask:0xf bank_mask:0xf
	v_fmac_f32_dpp v64, v76, v6 row_newbcast:2 row_mask:0xf bank_mask:0xf
	v_fmac_f32_dpp v9, v74, v72 row_newbcast:5 row_mask:0xf bank_mask:0xf
	v_fmac_f32_dpp v65, v76, v7 row_newbcast:3 row_mask:0xf bank_mask:0xf
	v_fmac_f32_dpp v10, v74, v72 row_newbcast:6 row_mask:0xf bank_mask:0xf
	v_fmac_f32_dpp v64, v76, v8 row_newbcast:4 row_mask:0xf bank_mask:0xf
	v_fmac_f32_dpp v11, v74, v72 row_newbcast:7 row_mask:0xf bank_mask:0xf
	v_fmac_f32_dpp v65, v76, v9 row_newbcast:5 row_mask:0xf bank_mask:0xf
	v_fmac_f32_dpp v12, v74, v72 row_newbcast:8 row_mask:0xf bank_mask:0xf
	v_fmac_f32_dpp v64, v76, v10 row_newbcast:6 row_mask:0xf bank_mask:0xf
	v_fmac_f32_dpp v13, v74, v72 row_newbcast:9 row_mask:0xf bank_mask:0xf
	v_fmac_f32_dpp v65, v76, v11 row_newbcast:7 row_mask:0xf bank_mask:0xf
	v_fmac_f32_dpp v14, v74, v72 row_newbcast:10 row_mask:0xf bank_mask:0xf
	v_fmac_f32_dpp v64, v76, v12 row_newbcast:8 row_mask:0xf bank_mask:0xf
	v_fmac_f32_dpp v15, v74, v72 row_newbcast:11 row_mask:0xf bank_mask:0xf
	v_fmac_f32_dpp v65, v76, v13 row_newbcast:9 row_mask:0xf bank_mask:0xf
	v_fmac_f32_dpp v16, v74, v72 row_newbcast:12 row_mask:0xf bank_mask:0xf
	v_fmac_f32_dpp v64, v76, v14 row_newbcast:10 row_mask:0xf bank_mask:0xf
	v_fmac_f32_dpp v17, v74, v72 row_newbcast:13 row_mask:0xf bank_mask:0xf
	v_fmac_f32_dpp v65, v76, v15 row_newbcast:11 row_mask:0xf bank_mask:0xf
	v_fmac_f32_dpp v18, v74, v72 row_newbcast:14 row_mask:0xf bank_mask:0xf
	v_fmac_f32_dpp v64, v76, v16 row_newbcast:12 row_mask:0xf bank_mask:0xf
	v_fmac_f32_dpp v19, v74, v72 row_newbcast:15 row_mask:0xf bank_mask:0xf
	v_fmac_f32_dpp v65, v76, v17 row_newbcast:13 row_mask:0xf bank_mask:0xf
	v_fmac_f32_dpp v64, v76, v18 row_newbcast:14 row_mask:0xf bank_mask:0xf
	v_fmac_f32_dpp v65, v76, v19 row_newbcast:15 row_mask:0xf bank_mask:0xf
	ds_read2st64_b32 v[26:27], v3 offset0:30 offset1:31
	ds_read2st64_b32 v[28:29], v3 offset0:32 offset1:33
	ds_read_b32 v30, v3 offset:8704
	ds_read_b32 v85, v2 offset:7680
	v_mul_f32_dpp v0, v77, v4 row_newbcast:0 row_mask:0xf bank_mask:0xf
	v_mul_f32_dpp v1, v77, v5 row_newbcast:1 row_mask:0xf bank_mask:0xf
	v_fmac_f32_dpp v4, v79, v87 row_newbcast:0 row_mask:0xf bank_mask:0xf
	v_fmac_f32_dpp v0, v77, v6 row_newbcast:2 row_mask:0xf bank_mask:0xf
	v_fmac_f32_dpp v5, v79, v87 row_newbcast:1 row_mask:0xf bank_mask:0xf
	v_fmac_f32_dpp v1, v77, v7 row_newbcast:3 row_mask:0xf bank_mask:0xf
	v_fmac_f32_dpp v6, v79, v87 row_newbcast:2 row_mask:0xf bank_mask:0xf
	v_fmac_f32_dpp v0, v77, v8 row_newbcast:4 row_mask:0xf bank_mask:0xf
	v_fmac_f32_dpp v7, v79, v87 row_newbcast:3 row_mask:0xf bank_mask:0xf
	v_fmac_f32_dpp v1, v77, v9 row_newbcast:5 row_mask:0xf bank_mask:0xf
	v_fmac_f32_dpp v8, v79, v87 row_newbcast:4 row_mask:0xf bank_mask:0xf
	v_fmac_f32_dpp v0, v77, v10 row_newbcast:6 row_mask:0xf bank_mask:0xf
	v_fmac_f32_dpp v9, v79, v87 row_newbcast:5 row_mask:0xf bank_mask:0xf
	v_fmac_f32_dpp v1, v77, v11 row_newbcast:7 row_mask:0xf bank_mask:0xf
	v_fmac_f32_dpp v10, v79, v87 row_newbcast:6 row_mask:0xf bank_mask:0xf
	v_fmac_f32_dpp v0, v77, v12 row_newbcast:8 row_mask:0xf bank_mask:0xf
	v_fmac_f32_dpp v11, v79, v87 row_newbcast:7 row_mask:0xf bank_mask:0xf
	v_fmac_f32_dpp v1, v77, v13 row_newbcast:9 row_mask:0xf bank_mask:0xf
	v_fmac_f32_dpp v12, v79, v87 row_newbcast:8 row_mask:0xf bank_mask:0xf
	v_fmac_f32_dpp v0, v77, v14 row_newbcast:10 row_mask:0xf bank_mask:0xf
	v_fmac_f32_dpp v13, v79, v87 row_newbcast:9 row_mask:0xf bank_mask:0xf
	v_fmac_f32_dpp v1, v77, v15 row_newbcast:11 row_mask:0xf bank_mask:0xf
	v_fmac_f32_dpp v14, v79, v87 row_newbcast:10 row_mask:0xf bank_mask:0xf
	v_fmac_f32_dpp v0, v77, v16 row_newbcast:12 row_mask:0xf bank_mask:0xf
	v_fmac_f32_dpp v15, v79, v87 row_newbcast:11 row_mask:0xf bank_mask:0xf
	v_fmac_f32_dpp v1, v77, v17 row_newbcast:13 row_mask:0xf bank_mask:0xf
	v_fmac_f32_dpp v16, v79, v87 row_newbcast:12 row_mask:0xf bank_mask:0xf
	v_fmac_f32_dpp v0, v77, v18 row_newbcast:14 row_mask:0xf bank_mask:0xf
	v_fmac_f32_dpp v17, v79, v87 row_newbcast:13 row_mask:0xf bank_mask:0xf
	v_fmac_f32_dpp v1, v77, v19 row_newbcast:15 row_mask:0xf bank_mask:0xf
	v_fmac_f32_dpp v18, v79, v87 row_newbcast:14 row_mask:0xf bank_mask:0xf
	v_fmac_f32_dpp v19, v79, v87 row_newbcast:15 row_mask:0xf bank_mask:0xf
	v_add_f32_e32 v68, v0, v1
	v_add_f32_e32 v69, v0, v1
	s_waitcnt lgkmcnt(4)
	v_mul_f32_e32 v73, v20, v82
	v_permlane32_swap_b32_e32 v68, v69
	v_mul_f32_e32 v81, v82, v23
	v_add_f32_e32 v70, v68, v69
	v_add_f32_e32 v71, v68, v69
	v_rcp_f32_e32 v83, v81
	v_mul_f32_e32 v76, v24, v81
	v_permlane16_swap_b32_e32 v70, v71
	v_add_f32_e32 v72, v70, v71
	v_mul_f32_e32 v75, v22, v83
	v_mul_f32_e32 v74, v21, v83
	v_fmac_f32_dpp v4, v78, v72 row_newbcast:0 row_mask:0xf bank_mask:0xf
	v_fmac_f32_dpp v5, v78, v72 row_newbcast:1 row_mask:0xf bank_mask:0xf
	v_fmac_f32_dpp v6, v78, v72 row_newbcast:2 row_mask:0xf bank_mask:0xf
	v_mul_f32_dpp v66, v80, v4 row_newbcast:0 row_mask:0xf bank_mask:0xf
	v_fmac_f32_dpp v7, v78, v72 row_newbcast:3 row_mask:0xf bank_mask:0xf
	v_mul_f32_dpp v67, v80, v5 row_newbcast:1 row_mask:0xf bank_mask:0xf
	v_fmac_f32_dpp v8, v78, v72 row_newbcast:4 row_mask:0xf bank_mask:0xf
	v_fmac_f32_dpp v66, v80, v6 row_newbcast:2 row_mask:0xf bank_mask:0xf
	v_fmac_f32_dpp v9, v78, v72 row_newbcast:5 row_mask:0xf bank_mask:0xf
	v_fmac_f32_dpp v67, v80, v7 row_newbcast:3 row_mask:0xf bank_mask:0xf
	v_fmac_f32_dpp v10, v78, v72 row_newbcast:6 row_mask:0xf bank_mask:0xf
	v_fmac_f32_dpp v66, v80, v8 row_newbcast:4 row_mask:0xf bank_mask:0xf
	v_fmac_f32_dpp v11, v78, v72 row_newbcast:7 row_mask:0xf bank_mask:0xf
	v_fmac_f32_dpp v67, v80, v9 row_newbcast:5 row_mask:0xf bank_mask:0xf
	v_fmac_f32_dpp v12, v78, v72 row_newbcast:8 row_mask:0xf bank_mask:0xf
	v_fmac_f32_dpp v66, v80, v10 row_newbcast:6 row_mask:0xf bank_mask:0xf
	v_fmac_f32_dpp v13, v78, v72 row_newbcast:9 row_mask:0xf bank_mask:0xf
	v_fmac_f32_dpp v67, v80, v11 row_newbcast:7 row_mask:0xf bank_mask:0xf
	v_fmac_f32_dpp v14, v78, v72 row_newbcast:10 row_mask:0xf bank_mask:0xf
	v_fmac_f32_dpp v66, v80, v12 row_newbcast:8 row_mask:0xf bank_mask:0xf
	v_fmac_f32_dpp v15, v78, v72 row_newbcast:11 row_mask:0xf bank_mask:0xf
	v_fmac_f32_dpp v67, v80, v13 row_newbcast:9 row_mask:0xf bank_mask:0xf
	v_fmac_f32_dpp v16, v78, v72 row_newbcast:12 row_mask:0xf bank_mask:0xf
	v_fmac_f32_dpp v66, v80, v14 row_newbcast:10 row_mask:0xf bank_mask:0xf
	v_fmac_f32_dpp v17, v78, v72 row_newbcast:13 row_mask:0xf bank_mask:0xf
	v_fmac_f32_dpp v67, v80, v15 row_newbcast:11 row_mask:0xf bank_mask:0xf
	v_fmac_f32_dpp v18, v78, v72 row_newbcast:14 row_mask:0xf bank_mask:0xf
	v_fmac_f32_dpp v66, v80, v16 row_newbcast:12 row_mask:0xf bank_mask:0xf
	v_fmac_f32_dpp v19, v78, v72 row_newbcast:15 row_mask:0xf bank_mask:0xf
	v_fmac_f32_dpp v67, v80, v17 row_newbcast:13 row_mask:0xf bank_mask:0xf
	v_fmac_f32_dpp v66, v80, v18 row_newbcast:14 row_mask:0xf bank_mask:0xf
	v_fmac_f32_dpp v67, v80, v19 row_newbcast:15 row_mask:0xf bank_mask:0xf
	v_add_f32_e32 v60, v60, v61
	v_add_f32_e32 v62, v62, v63
	v_add_f32_e32 v64, v64, v65
	v_add_f32_e32 v66, v66, v67
	v_add_u32_e32 v2, 0x1800, v2
	v_add_u32_e32 v3, 0x1800, v3
	v_permlane32_swap_b32_e32 v60, v62
	v_permlane32_swap_b32_e32 v64, v66
	v_add_f32_e32 v60, v60, v62
	v_add_f32_e32 v64, v64, v66
	s_add_i32 s7, s7, 1
	s_nop 1
	v_permlane16_swap_b32_e32 v60, v64
	v_add_f32_e32 v60, v60, v64
	v_cvt_pk_bf16_f32 v60, v60, v39
	global_store_short v52, v60, s[4:5]
	s_add_u32 s4, s4, 0x1000
	s_addc_u32 s5, s5, 0
	s_cmp_lt_u32 s7, 8
	s_cbranch_scc1 .Lsc_it
	s_waitcnt lgkmcnt(0)
	s_barrier
	s_add_i32 s6, s6, 1
	s_cmp_lt_u32 s6, 64
	s_cbranch_scc1 .Lsc_blk
	s_branch .LBB0_871
